# gdn-prep step B (KK^T/QK^T): all four k-block B fragments of a column group read up front (spare VGPRs, counted waits); on top of prep5
# baseline (speedup 1.0000x reference)
; #define LAS __attribute__((address_space(3)))
; __device__ __forceinline__ unsigned f2bf(float f) { unsigned u = __builtin_bit_cast(unsigned, f); return (u + 0x7fffu + ((u >> 16) & 1u)) >> 16; }
; __device__ __forceinline__ void gdn_prep_phase(const Frame& F0, const Args& a0, int l) {
;     ...
; #pragma unroll
;             for (int kb = 0; kb < 4; ++kb) { aK[kb] = *(const LAS bf16x8*)(lds + GD_KS + trow * GD_PITCH + (32 * kb + 8 * g) * 2); aQ[kb] = *(const LAS bf16x8*)(lds + GD_QS + trow * GD_PITCH + (32 * kb + 8 * g) * 2); }
;             LAS unsigned char* AD = lds + GD_AD + d * 17408; LAS unsigned char* QKB = lds + GD_QKB + d * 9216;
;             float gpv[4], btv[4];
; #pragma unroll
;             for (int r = 0; r < 4; ++r) { gpv[r] = gcs[d * 64 + 16 * rt + 4 * g + r]; btv[r] = bts[d * 64 + 16 * rt + 4 * g + r]; }
; #pragma unroll
;             for (int ct = 0; ct < 4; ++ct) {
;                 if (ct <= rt) {
;                     const int pcol = 16 * ct + i, tcol = d ? 63 - pcol : pcol;
;                     f32x4 kk = (f32x4){0.f, 0.f, 0.f, 0.f}, qk = (f32x4){0.f, 0.f, 0.f, 0.f};
; #pragma unroll
;                     for (int kb = 0; kb < 4; ++kb) { const bf16x8 bK = *(const LAS bf16x8*)(lds + GD_KS + tcol * GD_PITCH + (32 * kb + 8 * g) * 2);
;                         kk = __builtin_amdgcn_mfma_f32_16x16x32_bf16(aK[kb], bK, kk, 0, 0, 0); qk = __builtin_amdgcn_mfma_f32_16x16x32_bf16(aQ[kb], bK, qk, 0, 0, 0); }
;                     const int pq = 16 * ct + i; const float gq = gcs[d * 64 + pq];
; #pragma unroll
;                     for (int r = 0; r < 4; ++r) { const int p = 16 * rt + 4 * g + r; const float dec = __expf(fminf(gpv[r] - gq, 0.f));
;                         *(LAS float*)(AD + p * GD_PITCH + pq * 4) = (pq < p) ? btv[r] * kk[r] * dec : 0.f;
;                         *(LAS bf16*)(QKB + p * GD_QKP + pq * 2) = (bf16)f2bf((pq <= p) ? qk[r] * dec : 0.f); }
.LBB0_409:
	s_waitcnt lgkmcnt(0)
	s_barrier
	v_mbcnt_lo_u32_b32 v60, -1, 0
	v_mbcnt_hi_u32_b32 v60, -1, v60
	s_movk_i32 s8, 0x90
	v_and_b32_e32 v106, 15, v60
	v_or_b32_e32 v20, s26, v106
	v_bitop3_b32 v21, v106, 63, s26 bitop3:0x36
	v_cndmask_b32_e64 v20, v21, v20, s[4:5]
	v_and_b32_e32 v21, -16, v60
	v_add_u32_e32 v107, 0, v21
	v_ashrrev_i32_e32 v113, 2, v60
	v_mad_u32_u24 v20, v20, s86, v107
	v_and_b32_e32 v114, -4, v113
	ds_read_b128 v[52:55], v20 offset:17408
	ds_read_b128 v[56:59], v20
	ds_read_b128 v[44:47], v20 offset:17472
	ds_read_b128 v[48:51], v20 offset:64
	ds_read_b128 v[36:39], v20 offset:17536
	ds_read_b128 v[40:43], v20 offset:128
	ds_read_b128 v[28:31], v20 offset:17600
	ds_read_b128 v[32:35], v20 offset:192
	v_add_u32_e32 v20, s7, v114
	v_bitop3_b32 v60, v60, 63, 15 bitop3:0x6c
	v_lshl_add_u32 v20, v20, 2, 0
	v_cndmask_b32_e64 v60, v60, v106, s[4:5]
	v_add_u32_e32 v21, 0x22c00, v20
	v_mad_u32_u24 v112, v60, s86, v107
	ds_read_b128 v[24:27], v21
	ds_read_b128 v[60:63], v112 offset:17408
	ds_read_b128 v[116:119], v112 offset:17472
	ds_read_b128 v[224:227], v112 offset:17536
	ds_read_b128 v[228:231], v112 offset:17600
	s_waitcnt lgkmcnt(3)
	v_mfma_f32_16x16x32_bf16 v[108:111], v[52:55], v[60:63], 0
	v_add_u32_e32 v20, 0x22e00, v20
	ds_read_b128 v[20:23], v20
	v_add_u32_e32 v105, s26, v114
	v_mfma_f32_16x16x32_bf16 v[60:63], v[56:59], v[60:63], 0
	v_cmp_lt_i32_e32 vcc, v106, v105
	v_lshl_add_u32 v104, v106, 1, s6
	s_waitcnt lgkmcnt(3)
	v_mfma_f32_16x16x32_bf16 v[108:111], v[44:47], v[116:119], v[108:111]
	v_mfma_f32_16x16x32_bf16 v[60:63], v[48:51], v[116:119], v[60:63]
	s_nop 0
	s_waitcnt lgkmcnt(2)
	v_mfma_f32_16x16x32_bf16 v[108:111], v[36:39], v[224:227], v[108:111]
	v_mfma_f32_16x16x32_bf16 v[60:63], v[40:43], v[224:227], v[60:63]
	s_nop 0
	s_waitcnt lgkmcnt(1)
	v_mfma_f32_16x16x32_bf16 v[120:123], v[28:31], v[228:231], v[108:111]
	s_nop 3
	v_lshlrev_b32_e32 v109, 2, v106
	v_add_u32_e32 v108, s96, v109
	ds_read_b32 v115, v108
	v_mfma_f32_16x16x32_bf16 v[60:63], v[32:35], v[228:231], v[60:63]
	v_mul_f32_e32 v111, v20, v120
	v_mul_f32_e32 v118, v21, v121
	s_waitcnt lgkmcnt(0)
	v_sub_f32_e32 v110, v24, v115
	v_min_f32_e32 v110, 0, v110
	v_mul_f32_e32 v110, 0x3fb8aa3b, v110
	v_exp_f32_e32 v110, v110
	s_nop 0
	v_mul_f32_e32 v111, v111, v110
	v_cndmask_b32_e32 v116, 0, v111, vcc
	v_cmp_gt_i32_e32 vcc, v106, v105
	v_mul_f32_e32 v60, v60, v110
	v_mul_lo_u32 v111, v105, s86
	v_cndmask_b32_e64 v60, v60, 0, vcc
	v_add3_u32 v117, s24, v109, v111
	v_bfe_u32 v109, v60, 16, 1
	v_mul_lo_u32 v110, v105, s8
	v_add3_u32 v60, v60, v109, s28
	v_add_u32_e32 v112, v104, v110
	ds_write_b16_d16_hi v112, v60
	v_sub_f32_e32 v60, v25, v115
	v_min_f32_e32 v60, 0, v60
	v_mul_f32_e32 v60, 0x3fb8aa3b, v60
	v_exp_f32_e32 v60, v60
	v_or_b32_e32 v109, 1, v105
	v_add_u32_e32 v117, 0xcc00, v117
	v_mul_f32_e32 v118, v118, v60
	v_cndmask_b32_e64 v118, v118, 0, vcc
	v_mul_f32_e32 v60, v61, v60
	v_cmp_le_i32_e32 vcc, v106, v109
	ds_write2_b32 v117, v116, v118 offset1:68
	v_mul_f32_e32 v116, v22, v122
	v_cndmask_b32_e32 v60, 0, v60, vcc
	v_bfe_u32 v61, v60, 16, 1
	v_add3_u32 v60, v60, v61, s28
	v_sub_f32_e32 v61, v26, v115
	v_min_f32_e32 v61, 0, v61
	v_mul_f32_e32 v61, 0x3fb8aa3b, v61
	v_exp_f32_e32 v61, v61
	ds_write_b16_d16_hi v112, v60 offset:144
	v_or_b32_e32 v60, 2, v105
	v_cmp_lt_i32_e32 vcc, v106, v60
	v_mul_f32_e32 v116, v116, v61
	v_mul_f32_e32 v61, v62, v61
	v_cndmask_b32_e32 v116, 0, v116, vcc
	v_cmp_le_i32_e32 vcc, v106, v60
	s_nop 1
	v_cndmask_b32_e32 v61, 0, v61, vcc
	v_bfe_u32 v62, v61, 16, 1
	v_add3_u32 v61, v61, v62, s28
	v_sub_f32_e32 v62, v27, v115
	v_min_f32_e32 v62, 0, v62
	v_mul_f32_e32 v62, 0x3fb8aa3b, v62
	v_exp_f32_e32 v62, v62
	ds_write_b16_d16_hi v112, v61 offset:288
	v_or_b32_e32 v61, 3, v105
	v_mul_f32_e32 v115, v23, v123
	v_cmp_lt_i32_e32 vcc, v106, v61
	v_mul_f32_e32 v115, v115, v62
	v_mul_f32_e32 v62, v63, v62
	v_cndmask_b32_e32 v115, 0, v115, vcc
	v_cmp_le_i32_e32 vcc, v106, v61
	ds_write2_b32 v117, v116, v115 offset0:136 offset1:204
	s_nop 0
	v_cndmask_b32_e32 v62, 0, v62, vcc
	v_bfe_u32 v63, v62, 16, 1
	v_add3_u32 v63, v62, v63, s28
	v_add_u32_e32 v62, 0x1b0, v110
	v_add_u32_e32 v115, v104, v62
	s_andn2_b64 vcc, exec, s[94:95]
	ds_write_b16_d16_hi v115, v63
	s_cbranch_vccnz .LBB0_472
; #define LAS __attribute__((address_space(3)))
; __device__ __forceinline__ unsigned f2bf(float f) { unsigned u = __builtin_bit_cast(unsigned, f); return (u + 0x7fffu + ((u >> 16) & 1u)) >> 16; }
; __device__ __forceinline__ void gdn_prep_phase(const Frame& F0, const Args& a0, int l) {
;     ...
; #pragma unroll
;             for (int ct = 0; ct < 4; ++ct) {
;                 if (ct <= rt) {
;                     const int pcol = 16 * ct + i, tcol = d ? 63 - pcol : pcol;
;                     f32x4 kk = (f32x4){0.f, 0.f, 0.f, 0.f}, qk = (f32x4){0.f, 0.f, 0.f, 0.f};
; #pragma unroll
;                     for (int kb = 0; kb < 4; ++kb) { const bf16x8 bK = *(const LAS bf16x8*)(lds + GD_KS + tcol * GD_PITCH + (32 * kb + 8 * g) * 2);
;                         kk = __builtin_amdgcn_mfma_f32_16x16x32_bf16(aK[kb], bK, kk, 0, 0, 0); qk = __builtin_amdgcn_mfma_f32_16x16x32_bf16(aQ[kb], bK, qk, 0, 0, 0); }
;                     const int pq = 16 * ct + i; const float gq = gcs[d * 64 + pq];
; #pragma unroll
;                     for (int r = 0; r < 4; ++r) { const int p = 16 * rt + 4 * g + r; const float dec = __expf(fminf(gpv[r] - gq, 0.f));
;                         *(LAS float*)(AD + p * GD_PITCH + pq * 4) = (pq < p) ? btv[r] * kk[r] * dec : 0.f;
;                         *(LAS bf16*)(QKB + p * GD_QKP + pq * 2) = (bf16)f2bf((pq <= p) ? qk[r] * dec : 0.f); }
	v_or_b32_e32 v115, 16, v106
	v_xor_b32_e32 v63, 47, v106
	v_cndmask_b32_e64 v63, v63, v115, s[4:5]
	v_mad_u32_u24 v63, v63, s86, v107
	ds_read_b128 v[116:119], v63 offset:17408
	ds_read_b128 v[124:127], v63 offset:17472
	ds_read_b128 v[232:235], v63 offset:17536
	ds_read_b128 v[236:239], v63 offset:17600
	v_cmp_lt_i32_e32 vcc, v115, v105
	s_waitcnt lgkmcnt(3)
	v_mfma_f32_16x16x32_bf16 v[120:123], v[52:55], v[116:119], 0
	v_mfma_f32_16x16x32_bf16 v[116:119], v[56:59], v[116:119], 0
	s_waitcnt lgkmcnt(2)
	v_mfma_f32_16x16x32_bf16 v[120:123], v[44:47], v[124:127], v[120:123]
	v_mfma_f32_16x16x32_bf16 v[116:119], v[48:51], v[124:127], v[116:119]
	s_nop 0
	s_waitcnt lgkmcnt(1)
	v_mfma_f32_16x16x32_bf16 v[120:123], v[36:39], v[232:235], v[120:123]
	v_mfma_f32_16x16x32_bf16 v[116:119], v[40:43], v[232:235], v[116:119]
	s_nop 0
	v_lshl_add_u32 v63, v115, 1, s6
	s_waitcnt lgkmcnt(0)
	v_mfma_f32_16x16x32_bf16 v[120:123], v[28:31], v[236:239], v[120:123]
	v_mfma_f32_16x16x32_bf16 v[116:119], v[32:35], v[236:239], v[116:119]
	ds_read_b32 v124, v108 offset:64
	s_nop 5
	v_mul_f32_e32 v120, v20, v120
	v_mul_f32_e32 v121, v21, v121
	v_lshlrev_b32_e32 v125, 2, v115
	v_add3_u32 v125, s24, v125, v111
	s_waitcnt lgkmcnt(0)
	v_sub_f32_e32 v126, v24, v124
	v_min_f32_e32 v126, 0, v126
	v_mul_f32_e32 v126, 0x3fb8aa3b, v126
	v_exp_f32_e32 v126, v126
	v_add_u32_e32 v125, 0xcc00, v125
	v_mul_f32_e32 v120, v120, v126
	v_cndmask_b32_e32 v120, 0, v120, vcc
	v_cmp_gt_i32_e32 vcc, v115, v105
	v_mul_f32_e32 v116, v116, v126
	s_nop 0
	v_cndmask_b32_e64 v116, v116, 0, vcc
	v_bfe_u32 v126, v116, 16, 1
	v_add3_u32 v116, v116, v126, s28
	v_add_u32_e32 v126, v63, v110
	ds_write_b16_d16_hi v126, v116
	v_sub_f32_e32 v116, v25, v124
	v_min_f32_e32 v116, 0, v116
	v_mul_f32_e32 v116, 0x3fb8aa3b, v116
	v_exp_f32_e32 v116, v116
	s_nop 0
	v_mul_f32_e32 v121, v121, v116
	v_cndmask_b32_e64 v121, v121, 0, vcc
	v_mul_f32_e32 v116, v117, v116
	v_cmp_le_i32_e32 vcc, v115, v109
	ds_write2_b32 v125, v120, v121 offset1:68
	s_nop 0
	v_cndmask_b32_e32 v116, 0, v116, vcc
	v_bfe_u32 v117, v116, 16, 1
	v_add3_u32 v116, v116, v117, s28
	ds_write_b16_d16_hi v126, v116 offset:144
	v_sub_f32_e32 v116, v26, v124
	v_min_f32_e32 v116, 0, v116
	v_mul_f32_e32 v116, 0x3fb8aa3b, v116
	v_exp_f32_e32 v116, v116
	v_mul_f32_e32 v117, v22, v122
	v_cmp_lt_i32_e32 vcc, v115, v60
	v_mul_f32_e32 v117, v117, v116
	s_nop 0
	v_cndmask_b32_e32 v117, 0, v117, vcc
	v_mul_f32_e32 v116, v118, v116
	v_cmp_le_i32_e32 vcc, v115, v60
	s_nop 1
	v_cndmask_b32_e32 v116, 0, v116, vcc
	v_bfe_u32 v118, v116, 16, 1
	v_add3_u32 v116, v116, v118, s28
	ds_write_b16_d16_hi v126, v116 offset:288
	v_sub_f32_e32 v116, v27, v124
	v_min_f32_e32 v116, 0, v116
	v_mul_f32_e32 v116, 0x3fb8aa3b, v116
	v_exp_f32_e32 v116, v116
	v_mul_f32_e32 v118, v23, v123
	v_cmp_lt_i32_e32 vcc, v115, v61
	v_mul_f32_e32 v118, v118, v116
	s_nop 0
	v_cndmask_b32_e32 v118, 0, v118, vcc
	v_mul_f32_e32 v116, v119, v116
	v_cmp_le_i32_e32 vcc, v115, v61
	ds_write2_b32 v125, v117, v118 offset0:136 offset1:204
	s_nop 0
	v_cndmask_b32_e32 v115, 0, v116, vcc
	v_bfe_u32 v116, v115, 16, 1
	v_add3_u32 v115, v115, v116, s28
	v_lshrrev_b32_e32 v115, 16, v115
	s_cbranch_execnz .LBB0_412

; #define LAS __attribute__((address_space(3)))
; __device__ __forceinline__ unsigned f2bf(float f) { unsigned u = __builtin_bit_cast(unsigned, f); return (u + 0x7fffu + ((u >> 16) & 1u)) >> 16; }
; __device__ __forceinline__ void gdn_prep_phase(const Frame& F0, const Args& a0, int l) {
;     ...
; #pragma unroll
;             for (int ct = 0; ct < 4; ++ct) {
;                 if (ct <= rt) {
;                     const int pcol = 16 * ct + i, tcol = d ? 63 - pcol : pcol;
;                     f32x4 kk = (f32x4){0.f, 0.f, 0.f, 0.f}, qk = (f32x4){0.f, 0.f, 0.f, 0.f};
; #pragma unroll
;                     for (int kb = 0; kb < 4; ++kb) { const bf16x8 bK = *(const LAS bf16x8*)(lds + GD_KS + tcol * GD_PITCH + (32 * kb + 8 * g) * 2);
;                         kk = __builtin_amdgcn_mfma_f32_16x16x32_bf16(aK[kb], bK, kk, 0, 0, 0); qk = __builtin_amdgcn_mfma_f32_16x16x32_bf16(aQ[kb], bK, qk, 0, 0, 0); }
;                     const int pq = 16 * ct + i; const float gq = gcs[d * 64 + pq];
; #pragma unroll
;                     for (int r = 0; r < 4; ++r) { const int p = 16 * rt + 4 * g + r; const float dec = __expf(fminf(gpv[r] - gq, 0.f));
;                         *(LAS float*)(AD + p * GD_PITCH + pq * 4) = (pq < p) ? btv[r] * kk[r] * dec : 0.f;
;                         *(LAS bf16*)(QKB + p * GD_QKP + pq * 2) = (bf16)f2bf((pq <= p) ? qk[r] * dec : 0.f); }
.LBB0_412:
	v_add_u32_e32 v62, v63, v62
	s_andn2_b64 vcc, exec, s[78:79]
	s_mov_b64 s[8:9], -1
	ds_write_b16 v62, v115
	s_cbranch_vccnz .LBB0_416
	v_or_b32_e32 v62, 32, v106
	v_xor_b32_e32 v63, 31, v106
	v_cndmask_b32_e64 v63, v63, v62, s[4:5]
	v_mad_u32_u24 v63, v63, s86, v107
	ds_read_b128 v[114:117], v63 offset:17408
	ds_read_b128 v[122:125], v63 offset:17472
	ds_read_b128 v[240:243], v63 offset:17536
	ds_read_b128 v[244:247], v63 offset:17600
	v_cmp_lt_i32_e32 vcc, v62, v105
	v_lshlrev_b32_e32 v113, 1, v62
	s_waitcnt lgkmcnt(3)
	v_mfma_f32_16x16x32_bf16 v[118:121], v[52:55], v[114:117], 0
	v_add3_u32 v113, s6, v113, v110
	v_lshlrev_b32_e32 v104, 2, v62
	v_add3_u32 v104, s24, v104, v111
	v_mfma_f32_16x16x32_bf16 v[114:117], v[56:59], v[114:117], 0
	v_add_u32_e32 v104, 0xcc00, v104
	s_waitcnt lgkmcnt(2)
	v_mfma_f32_16x16x32_bf16 v[118:121], v[44:47], v[122:125], v[118:121]
	v_mfma_f32_16x16x32_bf16 v[114:117], v[48:51], v[122:125], v[114:117]
	s_nop 0
	s_waitcnt lgkmcnt(1)
	v_mfma_f32_16x16x32_bf16 v[118:121], v[36:39], v[240:243], v[118:121]
	v_mfma_f32_16x16x32_bf16 v[114:117], v[40:43], v[240:243], v[114:117]
	s_nop 0
	ds_read_b32 v63, v108 offset:128
	s_waitcnt lgkmcnt(1)
	v_mfma_f32_16x16x32_bf16 v[118:121], v[28:31], v[244:247], v[118:121]
	v_mfma_f32_16x16x32_bf16 v[114:117], v[32:35], v[244:247], v[114:117]
	s_waitcnt lgkmcnt(0)
	v_sub_f32_e32 v122, v24, v63
	v_min_f32_e32 v122, 0, v122
	v_mul_f32_e32 v122, 0x3fb8aa3b, v122
	v_exp_f32_e32 v122, v122
	s_nop 1
	v_mul_f32_e32 v118, v20, v118
	v_mul_f32_e32 v119, v21, v119
	v_mul_f32_e32 v118, v118, v122
	v_cndmask_b32_e32 v118, 0, v118, vcc
	v_cmp_gt_i32_e32 vcc, v62, v105
	v_mul_f32_e32 v114, v114, v122
	s_nop 0
	v_cndmask_b32_e64 v114, v114, 0, vcc
	v_bfe_u32 v122, v114, 16, 1
	v_add3_u32 v114, v114, v122, s28
	ds_write_b16_d16_hi v113, v114
	v_sub_f32_e32 v114, v25, v63
	v_min_f32_e32 v114, 0, v114
	v_mul_f32_e32 v114, 0x3fb8aa3b, v114
	v_exp_f32_e32 v114, v114
	s_nop 0
	v_mul_f32_e32 v119, v119, v114
	v_cndmask_b32_e64 v119, v119, 0, vcc
	v_mul_f32_e32 v114, v115, v114
	v_cmp_le_i32_e32 vcc, v62, v109
	ds_write2_b32 v104, v118, v119 offset1:68
	s_nop 0
	v_cndmask_b32_e32 v114, 0, v114, vcc
	v_bfe_u32 v115, v114, 16, 1
	v_add3_u32 v114, v114, v115, s28
	ds_write_b16_d16_hi v113, v114 offset:144
	v_sub_f32_e32 v114, v26, v63
	v_min_f32_e32 v114, 0, v114
	v_mul_f32_e32 v114, 0x3fb8aa3b, v114
	v_exp_f32_e32 v114, v114
	v_mul_f32_e32 v115, v22, v120
	v_sub_f32_e32 v63, v27, v63
	v_cmp_lt_i32_e32 vcc, v62, v60
	v_mul_f32_e32 v115, v115, v114
	v_min_f32_e32 v63, 0, v63
	v_cndmask_b32_e32 v115, 0, v115, vcc
	v_mul_f32_e32 v114, v116, v114
	v_cmp_le_i32_e32 vcc, v62, v60
	v_mul_f32_e32 v63, 0x3fb8aa3b, v63
	v_exp_f32_e32 v63, v63
	v_cndmask_b32_e32 v114, 0, v114, vcc
	v_bfe_u32 v116, v114, 16, 1
	v_add3_u32 v114, v114, v116, s28
	ds_write_b16_d16_hi v113, v114 offset:288
	v_mul_f32_e32 v114, v23, v121
	v_cmp_lt_i32_e32 vcc, v62, v61
	v_mul_f32_e32 v114, v114, v63
	v_mul_f32_e32 v63, v117, v63
	v_cndmask_b32_e32 v114, 0, v114, vcc
	v_cmp_le_i32_e32 vcc, v62, v61
	ds_write2_b32 v104, v115, v114 offset0:136 offset1:204
	s_nop 0
	v_cndmask_b32_e32 v62, 0, v63, vcc
	v_bfe_u32 v63, v62, 16, 1
	v_add3_u32 v62, v62, v63, s28
	ds_write_b16_d16_hi v113, v62 offset:432
	s_cbranch_execz .LBB0_417

; #define LAS __attribute__((address_space(3)))
; __device__ __forceinline__ unsigned f2bf(float f) { unsigned u = __builtin_bit_cast(unsigned, f); return (u + 0x7fffu + ((u >> 16) & 1u)) >> 16; }
; __device__ __forceinline__ void gdn_prep_phase(const Frame& F0, const Args& a0, int l) {
;     ...
;             for (int ct = 0; ct < 4; ++ct) {
;                 if (ct <= rt) {
;                     const int pcol = 16 * ct + i, tcol = d ? 63 - pcol : pcol;
;                     f32x4 kk = (f32x4){0.f, 0.f, 0.f, 0.f}, qk = (f32x4){0.f, 0.f, 0.f, 0.f};
; #pragma unroll
;                     for (int kb = 0; kb < 4; ++kb) { const bf16x8 bK = *(const LAS bf16x8*)(lds + GD_KS + tcol * GD_PITCH + (32 * kb + 8 * g) * 2);
;                         kk = __builtin_amdgcn_mfma_f32_16x16x32_bf16(aK[kb], bK, kk, 0, 0, 0); qk = __builtin_amdgcn_mfma_f32_16x16x32_bf16(aQ[kb], bK, qk, 0, 0, 0); }
;                     const int pq = 16 * ct + i; const float gq = gcs[d * 64 + pq];
; #pragma unroll
;                     for (int r = 0; r < 4; ++r) { const int p = 16 * rt + 4 * g + r; const float dec = __expf(fminf(gpv[r] - gq, 0.f));
;                         *(LAS float*)(AD + p * GD_PITCH + pq * 4) = (pq < p) ? btv[r] * kk[r] * dec : 0.f;
;                         *(LAS bf16*)(QKB + p * GD_QKP + pq * 2) = (bf16)f2bf((pq <= p) ? qk[r] * dec : 0.f); }
.LBB0_419:
	v_or_b32_e32 v62, 48, v106
	v_xor_b32_e32 v63, 15, v106
	v_cndmask_b32_e64 v63, v63, v62, s[4:5]
	v_mad_u32_u24 v63, v63, s86, v107
	ds_read_b128 v[112:115], v63 offset:17408
	ds_read_b128 v[248:251], v63 offset:17472
	ds_read_b128 v[252:255], v63 offset:17536
	ds_read_b128 v[196:199], v63 offset:17600
	v_cmp_lt_i32_e32 vcc, v62, v105
	s_waitcnt lgkmcnt(3)
	v_mfma_f32_16x16x32_bf16 v[52:55], v[52:55], v[112:115], 0
	v_mfma_f32_16x16x32_bf16 v[56:59], v[56:59], v[112:115], 0
	s_nop 0
	s_waitcnt lgkmcnt(2)
	v_mfma_f32_16x16x32_bf16 v[44:47], v[44:47], v[248:251], v[52:55]
	s_nop 3
	s_nop 0
	s_waitcnt lgkmcnt(1)
	v_mfma_f32_16x16x32_bf16 v[36:39], v[36:39], v[252:255], v[44:47]
	s_nop 2
	s_nop 0
	s_waitcnt lgkmcnt(0)
	v_mfma_f32_16x16x32_bf16 v[28:31], v[28:31], v[196:199], v[36:39]
	s_nop 2
	ds_read_b32 v36, v108 offset:192
	v_lshlrev_b32_e32 v38, 1, v62
	v_mfma_f32_16x16x32_bf16 v[48:51], v[48:51], v[248:251], v[56:59]
	s_nop 1
	v_mul_f32_e32 v20, v20, v28
	v_lshlrev_b32_e32 v37, 2, v62
	s_waitcnt lgkmcnt(0)
	v_sub_f32_e32 v24, v24, v36
	v_mfma_f32_16x16x32_bf16 v[40:43], v[40:43], v[252:255], v[48:51]
	v_min_f32_e32 v24, 0, v24
	v_mul_f32_e32 v24, 0x3fb8aa3b, v24
	v_exp_f32_e32 v24, v24
	v_mfma_f32_16x16x32_bf16 v[32:35], v[32:35], v[196:199], v[40:43]
	v_mul_f32_e32 v21, v21, v29
	v_add3_u32 v28, s24, v37, v111
	v_mul_f32_e32 v20, v20, v24
	v_cndmask_b32_e32 v20, 0, v20, vcc
	v_cmp_gt_i32_e32 vcc, v62, v105
	s_nop 2
	v_mul_f32_e32 v24, v32, v24
	v_cndmask_b32_e64 v24, v24, 0, vcc
	v_bfe_u32 v32, v24, 16, 1
	v_add3_u32 v24, v24, v32, s28
	v_add3_u32 v32, s6, v38, v110
	ds_write_b16_d16_hi v32, v24
	v_sub_f32_e32 v24, v25, v36
	v_min_f32_e32 v24, 0, v24
	v_mul_f32_e32 v24, 0x3fb8aa3b, v24
	v_exp_f32_e32 v24, v24
	v_add_u32_e32 v25, 0xcc00, v28
	v_mul_f32_e32 v21, v21, v24
	v_cndmask_b32_e64 v21, v21, 0, vcc
	ds_write2_b32 v25, v20, v21 offset1:68
	v_mul_f32_e32 v20, v33, v24
	v_cmp_le_i32_e32 vcc, v62, v109
	s_nop 1
	v_cndmask_b32_e32 v20, 0, v20, vcc
	v_bfe_u32 v21, v20, 16, 1
	v_add3_u32 v20, v20, v21, s28
	ds_write_b16_d16_hi v32, v20 offset:144
	v_sub_f32_e32 v20, v26, v36
	v_min_f32_e32 v20, 0, v20
	v_mul_f32_e32 v20, 0x3fb8aa3b, v20
	v_exp_f32_e32 v20, v20
	v_mul_f32_e32 v21, v22, v30
	v_cmp_lt_i32_e32 vcc, v62, v60
	v_mul_f32_e32 v21, v21, v20
	s_nop 0
	v_cndmask_b32_e32 v21, 0, v21, vcc
	v_mul_f32_e32 v20, v34, v20
	v_cmp_le_i32_e32 vcc, v62, v60
	s_nop 1
	v_cndmask_b32_e32 v20, 0, v20, vcc
	v_bfe_u32 v22, v20, 16, 1
	v_add3_u32 v20, v20, v22, s28
	ds_write_b16_d16_hi v32, v20 offset:288
	v_sub_f32_e32 v20, v27, v36
	v_min_f32_e32 v20, 0, v20
	v_mul_f32_e32 v20, 0x3fb8aa3b, v20
	v_exp_f32_e32 v20, v20
	v_mul_f32_e32 v22, v23, v31
	v_cmp_lt_i32_e32 vcc, v62, v61
	v_mul_f32_e32 v22, v22, v20
	s_nop 0
	v_cndmask_b32_e32 v22, 0, v22, vcc
	v_mul_f32_e32 v20, v35, v20
	v_cmp_le_i32_e32 vcc, v62, v61
	ds_write2_b32 v25, v21, v22 offset0:136 offset1:204
	s_nop 0
	v_cndmask_b32_e32 v20, 0, v20, vcc
	v_bfe_u32 v21, v20, 16, 1
	v_add3_u32 v20, v20, v21, s28
	ds_write_b16_d16_hi v32, v20 offset:432
